# P9 final-norm exchange: the four row-sum slots read in one batch (was three serialized round trips), stacked on v66
# speedup vs baseline: 1.0000x; 1.0000x over previous
.LBB0_2161:
	s_waitcnt vmcnt(0) lgkmcnt(0)
	s_barrier
	s_and_saveexec_b64 s[60:61], s[58:59]
	s_cbranch_execz .LBB0_2163
	v_lshl_add_u64 v[162:163], v[162:163], 4, s[44:45]
	s_waitcnt lgkmcnt(0)
	global_load_dword v165, v[162:163], off sc1
	global_load_dword v166, v[162:163], off offset:4 sc1
	global_load_dwordx2 v[162:163], v[162:163], off offset:8 sc1
	s_mov_b32 s17, 0x800000
	s_waitcnt vmcnt(2)
	v_add_f32_e32 v165, 0, v165
	s_waitcnt vmcnt(1)
	v_add_f32_e32 v165, v165, v166
	s_waitcnt vmcnt(0)
	v_add_f32_e32 v165, v165, v162
	v_add_f32_e32 v162, v165, v163
	v_fmamk_f32 v162, v162, 0x3a800000, v226
	v_cmp_gt_f32_e32 vcc, s17, v162
	v_mul_f32_e32 v163, 0x4b800000, v162
	s_nop 0
	v_cndmask_b32_e32 v162, v162, v163, vcc
	v_rsq_f32_e32 v162, v162
	s_nop 0
	v_mul_f32_e32 v163, 0x45800000, v162
	v_cndmask_b32_e32 v162, v162, v163, vcc
	v_add_u32_e32 v163, v220, v221
	ds_write_b32 v163, v162 offset:4096

.LBB0_2194:
	s_waitcnt vmcnt(0) lgkmcnt(0)
	s_barrier
	s_and_saveexec_b64 s[58:59], s[4:5]
	s_cbranch_execz .LBB0_2196
	v_lshl_add_u64 v[2:3], v[2:3], 4, s[44:45]
	global_load_dword v4, v[2:3], off sc1
	global_load_dword v5, v[2:3], off offset:4 sc1
	global_load_dwordx2 v[2:3], v[2:3], off offset:8 sc1
	s_mov_b32 s17, 0x800000
	s_waitcnt vmcnt(2)
	v_add_f32_e32 v4, 0, v4
	s_waitcnt vmcnt(1)
	v_add_f32_e32 v4, v4, v5
	s_waitcnt vmcnt(0)
	v_add_f32_e32 v4, v4, v2
	v_add_f32_e32 v2, v4, v3
	v_fmamk_f32 v2, v2, 0x3a800000, v226
	v_cmp_gt_f32_e32 vcc, s17, v2
	v_mul_f32_e32 v3, 0x4b800000, v2
	s_nop 0
	v_cndmask_b32_e32 v2, v2, v3, vcc
	v_rsq_f32_e32 v2, v2
	s_nop 0
	v_mul_f32_e32 v3, 0x45800000, v2
	v_cndmask_b32_e32 v2, v2, v3, vcc
	v_add_u32_e32 v3, v220, v221
	ds_write_b32 v3, v2 offset:4096
